# pre-tiled bf16 copy of projection weights made once at entry; projection GEMM B path loads bf16 directly (no per-tile cvt), bit-identical numerics
# speedup vs baseline: 1.0277x; 1.0277x over previous
_Z11mega_kernelILb1EEv6Paramsii:
	s_load_dwordx2 s[100:101], s[0:1], 0x198
	s_load_dword s3, s[0:1], 0x228
	s_load_dwordx2 s[4:5], s[0:1], 0x68
	s_load_dwordx2 s[6:7], s[0:1], 0xb0
	s_load_dwordx2 s[8:9], s[0:1], 0xb8
	s_load_dwordx2 s[10:11], s[0:1], 0xd8
	v_and_b32_e32 v1, 0x3ff, v0
	v_lshrrev_b32_e32 v2, 6, v1
	v_and_b32_e32 v3, 63, v1
	v_lshlrev_b32_e32 v2, 12, v2
	v_lshl_or_b32 v2, v3, 4, v2
	v_and_b32_e32 v3, 31, v1
	v_lshrrev_b32_e32 v4, 5, v1
	v_lshlrev_b32_e32 v3, 4, v3
	s_waitcnt lgkmcnt(0)
	s_mov_b32 s12, s2
.Lwc_loop:
	s_cmpk_gt_u32 s12, 0x2ff
	s_cbranch_scc1 .Lwc_done
	s_lshr_b32 s13, s12, 4
	s_and_b32 s14, s12, 15
	s_mov_b64 s[16:17], s[4:5]
	s_movk_i32 s15, 0x1c00
	s_mov_b32 s18, s13
	s_cmp_lt_u32 s13, 14
	s_cbranch_scc1 .Lwc_sel
	s_mov_b64 s[16:17], s[6:7]
	s_movk_i32 s15, 0x1000
	s_sub_u32 s18, s13, 14
	s_cmp_lt_u32 s13, 22
	s_cbranch_scc1 .Lwc_sel
	s_mov_b64 s[16:17], s[8:9]
	s_movk_i32 s15, 0x2400
	s_sub_u32 s18, s13, 22
	s_cmp_lt_u32 s13, 40
	s_cbranch_scc1 .Lwc_sel
	s_mov_b64 s[16:17], s[10:11]
	s_movk_i32 s15, 0x1000
	s_sub_u32 s18, s13, 40
.Lwc_sel:
	s_lshl_b32 s19, s14, 6
	s_mul_i32 s19, s19, s15
	s_lshl_b32 s20, s18, 9
	s_add_u32 s19, s19, s20
	s_add_u32 s16, s16, s19
	s_addc_u32 s17, s17, 0
	s_lshl_b32 s20, s15, 3
	v_mul_lo_u32 v5, v4, s20
	v_add_u32_e32 v5, v5, v3
	global_load_dwordx4 v[8:11], v5, s[16:17]
	s_add_u32 s16, s16, s15
	s_addc_u32 s17, s17, 0
	global_load_dwordx4 v[12:15], v5, s[16:17]
	s_add_u32 s16, s16, s15
	s_addc_u32 s17, s17, 0
	global_load_dwordx4 v[16:19], v5, s[16:17]
	s_add_u32 s16, s16, s15
	s_addc_u32 s17, s17, 0
	global_load_dwordx4 v[20:23], v5, s[16:17]
	s_add_u32 s16, s16, s15
	s_addc_u32 s17, s17, 0
	global_load_dwordx4 v[24:27], v5, s[16:17]
	s_add_u32 s16, s16, s15
	s_addc_u32 s17, s17, 0
	global_load_dwordx4 v[28:31], v5, s[16:17]
	s_add_u32 s16, s16, s15
	s_addc_u32 s17, s17, 0
	global_load_dwordx4 v[32:35], v5, s[16:17]
	s_add_u32 s16, s16, s15
	s_addc_u32 s17, s17, 0
	global_load_dwordx4 v[36:39], v5, s[16:17]
	s_lshl_b32 s19, s12, 14
	s_add_u32 s20, s100, s19
	s_addc_u32 s21, s101, 0
	s_waitcnt vmcnt(0)
	v_cvt_pk_bf16_f32 v40, v8, v12
	v_cvt_pk_bf16_f32 v41, v16, v20
	v_cvt_pk_bf16_f32 v42, v24, v28
	v_cvt_pk_bf16_f32 v43, v32, v36
	global_store_dwordx4 v2, v[40:43], s[20:21]
	v_cvt_pk_bf16_f32 v44, v9, v13
	v_cvt_pk_bf16_f32 v45, v17, v21
	v_cvt_pk_bf16_f32 v46, v25, v29
	v_cvt_pk_bf16_f32 v47, v33, v37
	global_store_dwordx4 v2, v[44:47], s[20:21] offset:1024
	v_cvt_pk_bf16_f32 v48, v10, v14
	v_cvt_pk_bf16_f32 v49, v18, v22
	v_cvt_pk_bf16_f32 v50, v26, v30
	v_cvt_pk_bf16_f32 v51, v34, v38
	global_store_dwordx4 v2, v[48:51], s[20:21] offset:2048
	v_cvt_pk_bf16_f32 v52, v11, v15
	v_cvt_pk_bf16_f32 v53, v19, v23
	v_cvt_pk_bf16_f32 v54, v27, v31
	v_cvt_pk_bf16_f32 v55, v35, v39
	global_store_dwordx4 v2, v[52:55], s[20:21] offset:3072
	s_add_u32 s12, s12, s3
	s_branch .Lwc_loop
.Lwc_done:
	s_load_dwordx4 s[72:75], s[0:1], 0x100
	s_mov_b32 s55, s2
	v_and_b32_e32 v250, 0x3ff, v0
	v_cmp_eq_u32_e64 s[4:5], 0, v250
	s_mov_b64 s[2:3], exec
	s_nop 0
	v_writelane_b32 v254, s4, 0
	s_nop 1
	v_writelane_b32 v254, s5, 1
	s_and_b64 s[4:5], s[2:3], s[4:5]
	s_mov_b64 exec, s[4:5]
	s_cbranch_execz .LBB0_2
	v_mov_b32_e32 v2, 0
	v_mov_b32_e32 v3, v2
	v_mov_b32_e32 v4, v2
	v_mov_b32_e32 v5, v2
	v_mov_b32_e32 v1, 0x10000
	ds_write_b128 v1, v[2:5]

.LBB0_180:
	s_ashr_i32 s2, s15, 31
	s_lshr_b32 s2, s2, 26
	s_add_i32 s6, s15, s2
	s_and_b32 s2, s6, 0xffffffc0
	s_sub_i32 s4, s15, s2
	s_ashr_i32 s5, s4, 31
	s_lshl_b64 s[2:3], s[4:5], 18
	s_add_u32 s16, s36, s2
	s_addc_u32 s17, s37, s3
	s_lshl_b32 s5, s6, 1
	v_readlane_b32 s56, v254, 18
	s_and_b32 s6, s5, 0xffffff80
	v_readlane_b32 s64, v254, 26
	v_readlane_b32 s65, v254, 27
	v_mov_b32_e32 v124, v250
	v_lshrrev_b32_e32 v248, 6, v250
	v_and_b32_e32 v249, 63, v250
	v_lshlrev_b32_e32 v248, 12, v248
	v_lshl_or_b32 v248, v249, 4, v248
	s_ashr_i32 s7, s6, 31
	s_lshl_b32 s98, s6, 11
	s_add_u32 s98, s100, s98
	s_addc_u32 s99, s101, 0
	v_readlane_b32 s66, v254, 28
	v_readlane_b32 s67, v254, 29
	v_readlane_b32 s68, v254, 30
	v_readlane_b32 s69, v254, 31
	v_readlane_b32 s70, v254, 32
	v_readlane_b32 s71, v254, 33
	s_mov_b64 s[20:21], s[64:65]
	s_movk_i32 s5, 0x3800
	v_and_b32_e32 v66, 31, v124
	v_ashrrev_i32_e32 v67, 5, v124
	s_lshl_b64 s[8:9], s[6:7], 2
	s_mov_b64 s[22:23], s[66:67]
	s_waitcnt vmcnt(62)
	v_lshlrev_b32_e32 v68, 2, v66
	v_mul_lo_u32 v1, v67, s5
	s_add_u32 s18, s22, s8
	v_or_b32_e32 v112, v68, v1
	s_addc_u32 s19, s23, s9
	v_lshlrev_b64 v[62:63], 2, v[112:113]
	v_lshl_add_u64 v[64:65], s[18:19], 0, v[62:63]
	s_movk_i32 s5, 0x1000
	v_add_co_u32_e32 v20, vcc, s5, v64
	s_movk_i32 s5, 0x3000
	s_nop 0
	v_addc_co_u32_e32 v21, vcc, 0, v65, vcc
	v_add_co_u32_e32 v24, vcc, s5, v64
	s_movk_i32 s5, 0x5000
	s_nop 0
	v_addc_co_u32_e32 v25, vcc, 0, v65, vcc
	v_add_co_u32_e32 v28, vcc, s5, v64
	s_movk_i32 s5, 0x7000
	s_nop 0
	v_addc_co_u32_e32 v29, vcc, 0, v65, vcc
	v_lshlrev_b32_e32 v0, 7, v124
	v_add_co_u32_e32 v32, vcc, s5, v64
	v_and_b32_e32 v0, 0xfffffc00, v0
	v_lshlrev_b32_e32 v69, 4, v124
	v_addc_co_u32_e32 v33, vcc, 0, v65, vcc
	s_mov_b32 s5, 0x8000
	v_add_u32_e32 v8, 0x10000, v0
	v_and_b32_e32 v4, 0x70, v69
	v_mov_b32_e32 v5, v113
	v_mov_b32_e32 v9, v113
	v_add_co_u32_e32 v36, vcc, s5, v64
	v_add_u32_e32 v2, 0x8000, v0
	v_add_u32_e32 v10, 0x18000, v0
	v_lshl_add_u64 v[12:13], s[16:17], 0, v[4:5]
	v_mov_b32_e32 v1, v113
	v_mov_b32_e32 v3, v113
	v_lshlrev_b64 v[54:55], 1, v[8:9]
	v_mov_b32_e32 v11, v113
	v_addc_co_u32_e32 v37, vcc, 0, v65, vcc
	s_mov_b32 s5, 0xa000
	v_lshl_add_u64 v[48:49], v[0:1], 1, v[12:13]
	v_lshlrev_b64 v[52:53], 1, v[2:3]
	v_lshl_add_u64 v[56:57], v[12:13], 0, v[54:55]
	v_lshlrev_b64 v[58:59], 1, v[10:11]
	v_add_co_u32_e32 v40, vcc, s5, v64
	v_lshl_add_u64 v[50:51], v[12:13], 0, v[52:53]
	global_load_dwordx4 v[0:3], v[48:49], off
	global_load_dwordx4 v[4:7], v[50:51], off
	v_lshl_add_u64 v[60:61], v[12:13], 0, v[58:59]
	global_load_dwordx4 v[8:11], v[56:57], off
	global_load_dwordx4 v[12:15], v[60:61], off
	v_addc_co_u32_e32 v41, vcc, 0, v65, vcc
	s_mov_b32 s5, 0xc000
	v_add_co_u32_e32 v44, vcc, s5, v64
	global_load_dwordx4 v[232:235], v248, s[98:99]
	global_load_dwordx4 v[236:239], v248, s[98:99] offset:1024
	global_load_dwordx4 v[240:243], v248, s[98:99] offset:2048
	global_load_dwordx4 v[244:247], v248, s[98:99] offset:3072
	s_add_u32 s98, s98, 0x4000
	s_addc_u32 s99, s99, 0
	s_nop 0
	s_nop 0
	s_nop 0
	s_nop 0
	s_nop 0
	v_addc_co_u32_e32 v45, vcc, 0, v65, vcc
	s_nop 0
	v_lshrrev_b32_e32 v72, 4, v124
	v_xor_b32_e32 v70, v72, v124
	v_lshlrev_b32_e32 v70, 4, v70
	v_and_b32_e32 v69, 0xffffff80, v69
	s_movk_i32 s5, 0x70
	v_and_or_b32 v128, v70, s5, v69
	s_waitcnt vmcnt(7)
	ds_write_b128 v128, v[0:3]
	s_waitcnt vmcnt(6)
	ds_write_b128 v128, v[4:7] offset:4096
	s_waitcnt vmcnt(5)
	ds_write_b128 v128, v[8:11] offset:8192
	s_waitcnt vmcnt(4)
	ds_write_b128 v128, v[12:15] offset:12288
	v_lshlrev_b32_e32 v4, 1, v124
	v_bitop3_b32 v4, v4, v67, 6 bitop3:0x6c
	s_mov_b32 s5, 0x70000
	v_and_b32_e32 v126, 15, v124
	v_bfe_u32 v125, v124, 6, 1
	v_lshlrev_b32_e32 v36, 3, v4
	v_lshlrev_b32_e32 v4, 4, v4
	v_lshl_add_u32 v4, v66, 9, v4
	s_waitcnt vmcnt(3)
	ds_write_b128 v4, v[232:235] offset:16384
	s_waitcnt vmcnt(2)
	ds_write_b128 v4, v[236:239] offset:16512
	v_or_b32_e32 v4, 2, v68
	v_lshrrev_b32_e32 v5, 1, v4
	v_bitop3_b32 v5, v5, v67, 7 bitop3:0x6c
	v_add_co_u32_e32 v16, vcc, s5, v64
	v_lshlrev_b32_e32 v30, 3, v5
	v_lshlrev_b32_e32 v5, 4, v5
	v_addc_co_u32_e32 v17, vcc, 0, v65, vcc
	s_mov_b32 s5, 0x71000
	v_lshlrev_b32_e32 v29, 6, v4
	v_lshl_add_u32 v4, v4, 7, v5
	v_add_co_u32_e32 v18, vcc, s5, v64
	s_waitcnt vmcnt(1)
	ds_write_b128 v4, v[240:243] offset:16384
	v_or_b32_e32 v4, 3, v68
	v_addc_co_u32_e32 v19, vcc, 0, v65, vcc
	s_mov_b32 s5, 0x73000
	v_lshrrev_b32_e32 v5, 1, v4
	v_add_co_u32_e32 v20, vcc, s5, v64
	v_bitop3_b32 v5, v5, v67, 7 bitop3:0x6c
	s_nop 0
	v_addc_co_u32_e32 v21, vcc, 0, v65, vcc
	s_mov_b32 s5, 0x75000
	v_lshlrev_b32_e32 v37, 3, v5
	v_lshlrev_b32_e32 v5, 4, v5
	v_add_co_u32_e32 v24, vcc, s5, v64
	v_lshlrev_b32_e32 v31, 6, v4
	v_lshl_add_u32 v4, v4, 7, v5
	v_addc_co_u32_e32 v25, vcc, 0, v65, vcc
	s_mov_b32 s5, 0x77000
	s_waitcnt vmcnt(0)
	ds_write_b128 v4, v[244:247] offset:16384
	s_waitcnt lgkmcnt(0)
	s_barrier
	global_load_dwordx4 v[0:3], v[48:49], off offset:128
	global_load_dwordx4 v[4:7], v[50:51], off offset:128
	global_load_dwordx4 v[8:11], v[56:57], off offset:128
	global_load_dwordx4 v[12:15], v[60:61], off offset:128
	global_load_dwordx4 v[232:235], v248, s[98:99]
	global_load_dwordx4 v[236:239], v248, s[98:99] offset:1024
	global_load_dwordx4 v[240:243], v248, s[98:99] offset:2048
	global_load_dwordx4 v[244:247], v248, s[98:99] offset:3072
	s_add_u32 s98, s98, 0x4000
	s_addc_u32 s99, s99, 0
	s_nop 0
	s_nop 0
	s_nop 0
	s_nop 0
	v_add_co_u32_e32 v24, vcc, s5, v64
	s_mov_b32 s5, 0x78000
	s_nop 0
	v_addc_co_u32_e32 v25, vcc, 0, v65, vcc
	v_add_co_u32_e32 v26, vcc, s5, v64
	s_mov_b32 s5, 0x7a000
	s_nop 0
	v_addc_co_u32_e32 v27, vcc, 0, v65, vcc
	v_add_co_u32_e32 v24, vcc, s5, v64
	s_mov_b32 s5, 0x7c000
	s_nop 0
	v_addc_co_u32_e32 v25, vcc, 0, v65, vcc
	v_add_co_u32_e32 v26, vcc, s5, v64
	v_ashrrev_i32_e32 v127, 7, v124
	s_nop 0
	v_addc_co_u32_e32 v27, vcc, 0, v65, vcc
	v_lshlrev_b32_e32 v24, 7, v126
	v_bfe_u32 v73, v124, 4, 2
	v_lshl_or_b32 v129, v127, 13, v24
	v_lshl_or_b32 v130, v125, 13, v24
	v_bfe_u32 v24, v124, 1, 3
	v_bitop3_b32 v25, v72, v24, 3 bitop3:0x6c
	v_bitop3_b32 v24, v73, v24, 4 bitop3:0x36
	v_lshlrev_b32_e32 v27, 3, v24
	v_and_b32_e32 v24, 7, v124
	v_lshlrev_b32_e32 v26, 3, v25
	v_lshlrev_b32_e32 v112, 4, v24
	v_bfe_u32 v24, v124, 3, 22
	v_mov_b32_e32 v25, v113
	s_add_u32 s2, s10, s2
	v_lshlrev_b64 v[24:25], 11, v[24:25]
	s_addc_u32 s3, s11, s3
	v_lshl_add_u64 v[114:115], s[2:3], 0, v[24:25]
	v_lshl_add_u64 v[116:117], s[2:3], 0, v[52:53]
	v_lshl_add_u64 v[118:119], s[2:3], 0, v[54:55]
	v_lshl_add_u64 v[120:121], s[2:3], 0, v[58:59]
	s_add_u32 s2, s12, s8
	v_lshlrev_b32_e32 v28, 8, v66
	s_addc_u32 s3, s13, s9
	v_lshl_add_u64 v[122:123], s[2:3], 0, v[62:63]
	v_lshlrev_b32_e32 v131, 1, v26
	v_lshlrev_b32_e32 v132, 1, v27
	v_lshlrev_b32_e32 v133, 1, v28
	v_lshlrev_b32_e32 v134, 1, v36
	v_lshlrev_b32_e32 v135, 1, v29
	v_lshlrev_b32_e32 v136, 1, v30
	v_lshlrev_b32_e32 v137, 1, v31
	v_lshlrev_b32_e32 v138, 1, v37
	s_mov_b32 s5, 0
	s_mov_b32 s7, 0
	v_mov_b32_e32 v24, v113
	v_mov_b32_e32 v25, v113
	v_mov_b32_e32 v26, v113
	v_mov_b32_e32 v27, v113
	v_mov_b32_e32 v28, v113
	v_mov_b32_e32 v29, v113
	v_mov_b32_e32 v30, v113
	v_mov_b32_e32 v31, v113
	v_mov_b32_e32 v36, v113
	v_mov_b32_e32 v37, v113
	v_mov_b32_e32 v38, v113
	v_mov_b32_e32 v39, v113
	v_mov_b32_e32 v44, v113
	v_mov_b32_e32 v45, v113
	v_mov_b32_e32 v46, v113
	v_mov_b32_e32 v47, v113
	v_mov_b32_e32 v64, v113
	v_mov_b32_e32 v65, v113
	v_mov_b32_e32 v66, v113
	v_mov_b32_e32 v67, v113
	v_mov_b32_e32 v76, v113
	v_mov_b32_e32 v77, v113
	v_mov_b32_e32 v78, v113
	v_mov_b32_e32 v79, v113
	v_mov_b32_e32 v84, v113
	v_mov_b32_e32 v85, v113
	v_mov_b32_e32 v86, v113
	v_mov_b32_e32 v87, v113
	v_mov_b32_e32 v88, v113
	v_mov_b32_e32 v89, v113
	v_mov_b32_e32 v90, v113
	v_mov_b32_e32 v91, v113
	v_mov_b32_e32 v96, v113
	v_mov_b32_e32 v97, v113
	v_mov_b32_e32 v98, v113
	v_mov_b32_e32 v99, v113
	v_mov_b32_e32 v100, v113
	v_mov_b32_e32 v101, v113
	v_mov_b32_e32 v102, v113
	v_mov_b32_e32 v103, v113
	v_mov_b32_e32 v104, v113
	v_mov_b32_e32 v105, v113
	v_mov_b32_e32 v106, v113
	v_mov_b32_e32 v107, v113
	v_mov_b32_e32 v108, v113
	v_mov_b32_e32 v109, v113
	v_mov_b32_e32 v110, v113
	v_mov_b32_e32 v111, v113
	v_mov_b32_e32 v52, v113
	v_mov_b32_e32 v53, v113
	v_mov_b32_e32 v54, v113
	v_mov_b32_e32 v55, v113
	v_mov_b32_e32 v56, v113
	v_mov_b32_e32 v57, v113
	v_mov_b32_e32 v58, v113
	v_mov_b32_e32 v59, v113
	v_mov_b32_e32 v60, v113
	v_mov_b32_e32 v61, v113
	v_mov_b32_e32 v62, v113
	v_mov_b32_e32 v63, v113
	v_mov_b32_e32 v72, v113
	v_mov_b32_e32 v73, v113
	v_mov_b32_e32 v74, v113
	v_mov_b32_e32 v75, v113
	v_readlane_b32 s57, v254, 19
	v_readlane_b32 s58, v254, 20
	v_readlane_b32 s59, v254, 21
	v_readlane_b32 s60, v254, 22
	v_readlane_b32 s61, v254, 23
	v_readlane_b32 s62, v254, 24
	v_readlane_b32 s63, v254, 25
	s_mov_b64 s[24:25], s[68:69]
	s_mov_b64 s[26:27], s[70:71]
	s_branch .LBB0_182

.LBB0_182:
	s_lshl_b32 s2, s7, 15
	v_add_u32_e32 v139, s2, v129
	v_or_b32_e32 v168, s2, v130
	s_setprio 1
	v_add_u32_e32 v169, v139, v131
	ds_read_b128 v[140:143], v169
	v_add_u32_e32 v156, v168, v131
	ds_read_b128 v[144:147], v156 offset:16384
	ds_read_b128 v[148:151], v156 offset:18432
	ds_read_b128 v[152:155], v156 offset:20480
	ds_read_b128 v[156:159], v156 offset:22528
	ds_read_b128 v[160:163], v169 offset:2048
	ds_read_b128 v[164:167], v169 offset:4096
	v_add_u32_e32 v139, v139, v132
	s_waitcnt lgkmcnt(5)
	v_mfma_f32_16x16x32_bf16 v[108:111], v[140:143], v[144:147], v[108:111]
	s_waitcnt lgkmcnt(4)
	v_mfma_f32_16x16x32_bf16 v[104:107], v[140:143], v[148:151], v[104:107]
	s_waitcnt lgkmcnt(3)
	v_mfma_f32_16x16x32_bf16 v[100:103], v[140:143], v[152:155], v[100:103]
	s_waitcnt lgkmcnt(2)
	v_mfma_f32_16x16x32_bf16 v[96:99], v[140:143], v[156:159], v[96:99]
	ds_read_b128 v[140:143], v169 offset:6144
	s_waitcnt lgkmcnt(2)
	v_mfma_f32_16x16x32_bf16 v[88:91], v[160:163], v[144:147], v[88:91]
	v_mfma_f32_16x16x32_bf16 v[84:87], v[160:163], v[148:151], v[84:87]
	v_mfma_f32_16x16x32_bf16 v[76:79], v[160:163], v[152:155], v[76:79]
	v_mfma_f32_16x16x32_bf16 v[64:67], v[160:163], v[156:159], v[64:67]
	s_waitcnt lgkmcnt(1)
	v_mfma_f32_16x16x32_bf16 v[44:47], v[164:167], v[144:147], v[44:47]
	v_mfma_f32_16x16x32_bf16 v[36:39], v[164:167], v[148:151], v[36:39]
	v_mfma_f32_16x16x32_bf16 v[28:31], v[164:167], v[152:155], v[28:31]
	v_mfma_f32_16x16x32_bf16 v[24:27], v[164:167], v[156:159], v[24:27]
	s_waitcnt lgkmcnt(0)
	v_mfma_f32_16x16x32_bf16 v[52:55], v[140:143], v[144:147], v[52:55]
	v_mfma_f32_16x16x32_bf16 v[56:59], v[140:143], v[148:151], v[56:59]
	v_mfma_f32_16x16x32_bf16 v[60:63], v[140:143], v[152:155], v[60:63]
	v_mfma_f32_16x16x32_bf16 v[72:75], v[140:143], v[156:159], v[72:75]
	ds_read_b128 v[140:143], v139
	v_add_u32_e32 v156, v168, v132
	ds_read_b128 v[144:147], v156 offset:16384
	ds_read_b128 v[148:151], v156 offset:18432
	ds_read_b128 v[152:155], v156 offset:20480
	ds_read_b128 v[156:159], v156 offset:22528
	ds_read_b128 v[160:163], v139 offset:2048
	ds_read_b128 v[164:167], v139 offset:4096
	s_waitcnt lgkmcnt(5)
	v_mfma_f32_16x16x32_bf16 v[108:111], v[140:143], v[144:147], v[108:111]
	s_waitcnt lgkmcnt(4)
	v_mfma_f32_16x16x32_bf16 v[104:107], v[140:143], v[148:151], v[104:107]
	s_waitcnt lgkmcnt(3)
	v_mfma_f32_16x16x32_bf16 v[100:103], v[140:143], v[152:155], v[100:103]
	s_waitcnt lgkmcnt(2)
	v_mfma_f32_16x16x32_bf16 v[96:99], v[140:143], v[156:159], v[96:99]
	ds_read_b128 v[140:143], v139 offset:6144
	s_waitcnt lgkmcnt(2)
	v_mfma_f32_16x16x32_bf16 v[88:91], v[160:163], v[144:147], v[88:91]
	v_mfma_f32_16x16x32_bf16 v[84:87], v[160:163], v[148:151], v[84:87]
	v_mfma_f32_16x16x32_bf16 v[76:79], v[160:163], v[152:155], v[76:79]
	v_mfma_f32_16x16x32_bf16 v[64:67], v[160:163], v[156:159], v[64:67]
	s_waitcnt lgkmcnt(1)
	v_mfma_f32_16x16x32_bf16 v[44:47], v[164:167], v[144:147], v[44:47]
	v_mfma_f32_16x16x32_bf16 v[36:39], v[164:167], v[148:151], v[36:39]
	v_mfma_f32_16x16x32_bf16 v[28:31], v[164:167], v[152:155], v[28:31]
	v_mfma_f32_16x16x32_bf16 v[24:27], v[164:167], v[156:159], v[24:27]
	s_waitcnt lgkmcnt(0)
	v_mfma_f32_16x16x32_bf16 v[52:55], v[140:143], v[144:147], v[52:55]
	v_mfma_f32_16x16x32_bf16 v[56:59], v[140:143], v[148:151], v[56:59]
	v_mfma_f32_16x16x32_bf16 v[60:63], v[140:143], v[152:155], v[60:63]
	v_mfma_f32_16x16x32_bf16 v[72:75], v[140:143], v[156:159], v[72:75]
	s_setprio 0
	s_cmpk_gt_u32 s5, 0x3bf
	s_cselect_b64 s[2:3], -1, 0
	s_and_b64 vcc, exec, s[2:3]
	s_cbranch_vccnz .LBB0_184
	s_lshl_b32 s8, s7, 14
	s_xor_b32 s8, s8, 0x4000
	s_lshl_b32 s8, s8, 1
	v_add_u32_e32 v139, s8, v128
	s_waitcnt vmcnt(7)
	ds_write_b128 v139, v[0:3]
	s_waitcnt vmcnt(6)
	ds_write_b128 v139, v[4:7] offset:4096
	s_waitcnt vmcnt(5)
	ds_write_b128 v139, v[8:11] offset:8192
	s_waitcnt vmcnt(4)
	ds_write_b128 v139, v[12:15] offset:12288
	v_add3_u32 v139, s8, v133, v134
	s_waitcnt vmcnt(3)
	ds_write_b128 v139, v[232:235] offset:16384
	s_waitcnt vmcnt(2)
	ds_write_b128 v139, v[236:239] offset:16512
	v_add3_u32 v139, s8, v135, v136
	s_waitcnt vmcnt(1)
	ds_write_b128 v139, v[240:243] offset:16384
	v_add3_u32 v139, s8, v137, v138
	s_waitcnt vmcnt(0)
	ds_write_b128 v139, v[244:247] offset:16384
.LBB0_184:
	s_cmpk_gt_u32 s5, 0x37f
	s_cbranch_scc1 .LBB0_181
	v_lshl_add_u64 v[0:1], v[114:115], 0, v[112:113]
	v_lshl_add_u64 v[4:5], v[116:117], 0, v[112:113]
	v_lshl_add_u64 v[8:9], v[118:119], 0, v[112:113]
	v_lshl_add_u64 v[12:13], v[120:121], 0, v[112:113]
	global_load_dwordx4 v[0:3], v[0:1], off
	global_load_dwordx4 v[4:7], v[4:5], off
	global_load_dwordx4 v[8:11], v[8:9], off
	global_load_dwordx4 v[12:15], v[12:13], off
	global_load_dwordx4 v[232:235], v248, s[98:99]
	global_load_dwordx4 v[236:239], v248, s[98:99] offset:1024
	global_load_dwordx4 v[240:243], v248, s[98:99] offset:2048
	global_load_dwordx4 v[244:247], v248, s[98:99] offset:3072
	s_add_u32 s98, s98, 0x4000
	s_addc_u32 s99, s99, 0
	s_branch .LBB0_181

.LBB0_756:
	v_readlane_b32 s76, v254, 34
	s_lshl_b32 s16, s0, 7
	v_readlane_b32 s88, v254, 46
	v_readlane_b32 s89, v254, 47
	v_mov_b32_e32 v138, v250
	v_lshrrev_b32_e32 v248, 6, v250
	v_and_b32_e32 v249, 63, v250
	v_lshlrev_b32_e32 v248, 12, v248
	v_lshl_or_b32 v248, v249, 4, v248
	s_ashr_i32 s17, s16, 31
	s_lshl_b32 s98, s16, 11
	s_add_u32 s98, s98, 0x380000
	s_add_u32 s98, s100, s98
	s_addc_u32 s99, s101, 0
	v_readlane_b32 s77, v254, 35
	v_readlane_b32 s78, v254, 36
	v_readlane_b32 s79, v254, 37
	v_readlane_b32 s80, v254, 38
	v_readlane_b32 s81, v254, 39
	v_readlane_b32 s82, v254, 40
	v_readlane_b32 s83, v254, 41
	v_readlane_b32 s84, v254, 42
	v_readlane_b32 s85, v254, 43
	v_readlane_b32 s86, v254, 44
	v_readlane_b32 s87, v254, 45
	v_readlane_b32 s90, v254, 48
	v_readlane_b32 s91, v254, 49
	s_mov_b64 s[20:21], s[88:89]
	s_lshl_b64 s[0:1], s[16:17], 2
	v_and_b32_e32 v64, 31, v138
	s_mov_b64 s[22:23], s[90:91]
	v_readlane_b32 s76, v253, 50
	v_ashrrev_i32_e32 v65, 5, v138
	v_lshlrev_b32_e32 v66, 2, v64
	s_add_u32 s10, s20, s0
	v_readlane_b32 s88, v253, 62
	v_readlane_b32 s89, v253, 63
	v_lshl_or_b32 v112, v65, 13, v66
	s_addc_u32 s11, s21, s1
	s_lshl_b64 s[18:19], s[2:3], 10
	s_lshl_b64 s[2:3], s[2:3], 11
	v_readlane_b32 s90, v255, 0
	v_readlane_b32 s91, v255, 1
	s_mov_b64 s[56:57], s[88:89]
	v_lshlrev_b64 v[58:59], 2, v[112:113]
	s_add_u32 s2, s56, s2
	s_waitcnt vmcnt(20)
	v_lshlrev_b32_e32 v48, 4, v138
	v_lshl_add_u64 v[60:61], s[10:11], 0, v[58:59]
	s_addc_u32 s3, s57, s3
	s_waitcnt vmcnt(3)
	v_and_b32_e32 v0, 0x70, v48
	v_mov_b32_e32 v1, v113
	v_add_co_u32_e32 v16, vcc, s14, v60
	v_lshl_add_u64 v[116:117], s[2:3], 0, v[0:1]
	s_nop 0
	v_addc_co_u32_e32 v17, vcc, 0, v61, vcc
	s_movk_i32 s2, 0x4000
	v_add_co_u32_e32 v24, vcc, s2, v60
	v_ashrrev_i32_e32 v126, 3, v138
	s_nop 0
	v_addc_co_u32_e32 v25, vcc, 0, v61, vcc
	s_movk_i32 s2, 0x6000
	v_add_u32_e32 v128, 64, v126
	v_add_co_u32_e32 v32, vcc, s2, v60
	v_add_u32_e32 v127, 32, v126
	v_add_u32_e32 v129, 0x60, v126
	v_lshlrev_b32_e32 v0, 10, v126
	v_lshlrev_b32_e32 v8, 10, v128
	v_mov_b32_e32 v9, v113
	v_addc_co_u32_e32 v33, vcc, 0, v61, vcc
	s_movk_i32 s2, 0x7000
	v_lshlrev_b64 v[118:119], 1, v[0:1]
	v_lshlrev_b32_e32 v0, 10, v127
	v_lshlrev_b64 v[122:123], 1, v[8:9]
	v_lshlrev_b32_e32 v40, 10, v129
	v_mov_b32_e32 v41, v113
	v_add_co_u32_e32 v36, vcc, s2, v60
	v_lshl_add_u64 v[52:53], v[116:117], 0, v[118:119]
	v_lshlrev_b64 v[120:121], 1, v[0:1]
	v_lshl_add_u64 v[56:57], v[116:117], 0, v[122:123]
	v_addc_co_u32_e32 v37, vcc, 0, v61, vcc
	v_lshlrev_b64 v[124:125], 1, v[40:41]
	v_lshl_add_u64 v[54:55], v[116:117], 0, v[120:121]
	global_load_dwordx4 v[0:3], v[52:53], off
	global_load_dwordx4 v[4:7], v[54:55], off
	s_nop 0
	s_nop 0
	s_nop 0
	s_nop 0
	s_nop 0
	v_lshl_add_u64 v[62:63], v[116:117], 0, v[124:125]
	s_nop 0
	global_load_dwordx4 v[40:43], v[56:57], off
	global_load_dwordx4 v[44:47], v[62:63], off
	global_load_dwordx4 v[232:235], v248, s[98:99]
	global_load_dwordx4 v[236:239], v248, s[98:99] offset:1024
	global_load_dwordx4 v[240:243], v248, s[98:99] offset:2048
	global_load_dwordx4 v[244:247], v248, s[98:99] offset:3072
	s_add_u32 s98, s98, 0x4000
	s_addc_u32 s99, s99, 0
	v_lshrrev_b32_e32 v112, 4, v138
	v_lshlrev_b32_e32 v49, 1, v138
	v_xor_b32_e32 v50, v112, v138
	v_and_b32_e32 v48, 0xffffff80, v48
	v_bitop3_b32 v67, v49, v65, 6 bitop3:0x6c
	v_lshlrev_b32_e32 v49, 4, v50
	s_movk_i32 s2, 0x70
	v_and_or_b32 v142, v49, s2, v48
	s_waitcnt vmcnt(7)
	ds_write_b128 v142, v[0:3]
	s_waitcnt vmcnt(6)
	ds_write_b128 v142, v[4:7] offset:4096
	s_waitcnt vmcnt(5)
	ds_write_b128 v142, v[40:43] offset:8192
	s_waitcnt vmcnt(4)
	ds_write_b128 v142, v[44:47] offset:12288
	v_lshlrev_b32_e32 v0, 4, v67
	v_lshl_add_u32 v4, v64, 9, v0
	s_waitcnt vmcnt(3)
	ds_write_b128 v4, v[232:235] offset:16384
	s_waitcnt vmcnt(2)
	ds_write_b128 v4, v[236:239] offset:16512
	v_or_b32_e32 v4, 2, v66
	v_lshrrev_b32_e32 v5, 1, v4
	v_bitop3_b32 v5, v5, v65, 7 bitop3:0x6c
	v_lshlrev_b32_e32 v8, 3, v5
	v_lshlrev_b32_e32 v5, 4, v5
	v_lshlrev_b32_e32 v7, 6, v4
	v_lshl_add_u32 v4, v4, 7, v5
	s_waitcnt vmcnt(1)
	ds_write_b128 v4, v[240:243] offset:16384
	v_or_b32_e32 v4, 3, v66
	v_lshrrev_b32_e32 v5, 1, v4
	v_bitop3_b32 v5, v5, v65, 7 bitop3:0x6c
	v_lshlrev_b32_e32 v10, 3, v5
	v_lshlrev_b32_e32 v5, 4, v5
	v_lshlrev_b32_e32 v9, 6, v4
	v_lshl_add_u32 v4, v4, 7, v5
	s_mov_b32 s2, 0x41000
	s_waitcnt vmcnt(0)
	ds_write_b128 v4, v[244:247] offset:16384
	v_add_co_u32_e32 v0, vcc, s2, v60
	s_mov_b32 s2, 0x43000
	s_nop 0
	v_addc_co_u32_e32 v1, vcc, 0, v61, vcc
	v_lshlrev_b32_e32 v146, 8, v64
	v_lshlrev_b32_e32 v6, 3, v67
	s_waitcnt lgkmcnt(0)
	s_barrier
	global_load_dwordx4 v[64:67], v[52:53], off offset:128
	global_load_dwordx4 v[68:71], v[54:55], off offset:128
	global_load_dwordx4 v[72:75], v[56:57], off offset:128
	global_load_dwordx4 v[76:79], v[62:63], off offset:128
	global_load_dwordx4 v[232:235], v248, s[98:99]
	global_load_dwordx4 v[236:239], v248, s[98:99] offset:1024
	global_load_dwordx4 v[240:243], v248, s[98:99] offset:2048
	global_load_dwordx4 v[244:247], v248, s[98:99] offset:3072
	s_add_u32 s98, s98, 0x4000
	s_addc_u32 s99, s99, 0
	v_add_co_u32_e32 v0, vcc, s2, v60
	s_mov_b32 s2, 0x45000
	s_nop 0
	v_addc_co_u32_e32 v1, vcc, 0, v61, vcc
	v_add_co_u32_e32 v0, vcc, s2, v60
	s_mov_b32 s2, 0x47000
	s_nop 0
	v_addc_co_u32_e32 v1, vcc, 0, v61, vcc
	v_add_co_u32_e32 v0, vcc, s2, v60
	v_readlane_b32 s86, v253, 60
	s_nop 0
	v_addc_co_u32_e32 v1, vcc, 0, v61, vcc
	v_readlane_b32 s87, v253, 61
	v_and_b32_e32 v141, 15, v138
	s_mov_b64 s[54:55], s[86:87]
	v_bfe_u32 v140, v138, 6, 1
	v_ashrrev_i32_e32 v139, 7, v138
	v_lshlrev_b32_e32 v0, 7, v141
	v_bfe_u32 v130, v138, 4, 2
	v_lshl_or_b32 v143, v139, 13, v0
	v_lshl_or_b32 v144, v140, 13, v0
	v_bfe_u32 v0, v138, 1, 3
	s_add_u32 s2, s54, s18
	v_bitop3_b32 v1, v112, v0, 3 bitop3:0x6c
	v_bitop3_b32 v0, v130, v0, 4 bitop3:0x36
	v_lshlrev_b32_e32 v4, 8, v129
	v_mov_b32_e32 v5, v113
	s_addc_u32 s3, s55, s19
	v_lshlrev_b32_e32 v12, 3, v0
	v_lshlrev_b32_e32 v112, 8, v126
	v_lshlrev_b32_e32 v0, 8, v127
	v_lshl_add_u64 v[126:127], v[4:5], 2, v[114:115]
	v_and_b32_e32 v4, 7, v138
	s_add_u32 s0, s12, s0
	v_lshlrev_b32_e32 v11, 3, v1
	v_mov_b32_e32 v1, v113
	v_lshlrev_b32_e32 v2, 8, v128
	v_mov_b32_e32 v3, v113
	v_lshlrev_b32_e32 v4, 5, v4
	s_addc_u32 s1, s13, s1
	v_mov_b32_e32 v16, 0
	s_mov_b32 s17, 0
	v_lshl_add_u64 v[128:129], s[2:3], 0, v[4:5]
	v_lshl_add_u64 v[130:131], s[0:1], 0, v[58:59]
	v_lshl_add_u64 v[132:133], v[2:3], 2, v[114:115]
	v_lshl_add_u64 v[134:135], v[0:1], 2, v[114:115]
	v_lshl_add_u64 v[136:137], v[112:113], 2, v[114:115]
	v_or_b32_e32 v118, 0x100, v118
	v_or_b32_e32 v120, 0x100, v120
	v_or_b32_e32 v122, 0x100, v122
	v_or_b32_e32 v124, 0x100, v124
	s_movk_i32 s20, 0xffc0
	v_lshlrev_b32_e32 v112, 1, v11
	v_lshlrev_b32_e32 v145, 1, v12
	v_lshlrev_b32_e32 v146, 1, v146
	v_lshlrev_b32_e32 v147, 1, v6
	v_lshlrev_b32_e32 v148, 1, v7
	v_lshlrev_b32_e32 v149, 1, v8
	v_lshlrev_b32_e32 v150, 1, v9
	v_lshlrev_b32_e32 v151, 1, v10
	v_mov_b32_e32 v17, v16
	v_mov_b32_e32 v18, v16
	v_mov_b32_e32 v19, v16
	v_mov_b32_e32 v20, v16
	v_mov_b32_e32 v21, v16
	v_mov_b32_e32 v22, v16
	v_mov_b32_e32 v23, v16
	v_mov_b32_e32 v24, v16
	v_mov_b32_e32 v25, v16
	v_mov_b32_e32 v26, v16
	v_mov_b32_e32 v27, v16
	v_mov_b32_e32 v28, v16
	v_mov_b32_e32 v29, v16
	v_mov_b32_e32 v30, v16
	v_mov_b32_e32 v31, v16
	v_mov_b32_e32 v32, v16
	v_mov_b32_e32 v33, v16
	v_mov_b32_e32 v34, v16
	v_mov_b32_e32 v35, v16
	v_mov_b32_e32 v36, v16
	v_mov_b32_e32 v37, v16
	v_mov_b32_e32 v38, v16
	v_mov_b32_e32 v39, v16
	v_mov_b32_e32 v40, v16
	v_mov_b32_e32 v41, v16
	v_mov_b32_e32 v42, v16
	v_mov_b32_e32 v43, v16
	v_mov_b32_e32 v44, v16
	v_mov_b32_e32 v45, v16
	v_mov_b32_e32 v46, v16
	v_mov_b32_e32 v47, v16
	v_mov_b32_e32 v48, v16
	v_mov_b32_e32 v49, v16
	v_mov_b32_e32 v50, v16
	v_mov_b32_e32 v51, v16
	v_mov_b32_e32 v52, v16
	v_mov_b32_e32 v53, v16
	v_mov_b32_e32 v54, v16
	v_mov_b32_e32 v55, v16
	v_mov_b32_e32 v56, v16
	v_mov_b32_e32 v57, v16
	v_mov_b32_e32 v58, v16
	v_mov_b32_e32 v59, v16
	v_mov_b32_e32 v60, v16
	v_mov_b32_e32 v61, v16
	v_mov_b32_e32 v62, v16
	v_mov_b32_e32 v63, v16
	v_mov_b32_e32 v8, v16
	v_mov_b32_e32 v9, v16
	v_mov_b32_e32 v10, v16
	v_mov_b32_e32 v11, v16
	v_mov_b32_e32 v4, v16
	v_mov_b32_e32 v5, v16
	v_mov_b32_e32 v6, v16
	v_mov_b32_e32 v7, v16
	v_mov_b32_e32 v0, v16
	v_mov_b32_e32 v1, v16
	v_mov_b32_e32 v2, v16
	v_mov_b32_e32 v3, v16
	v_mov_b32_e32 v12, v16
	v_mov_b32_e32 v13, v16
	v_mov_b32_e32 v14, v16
	v_mov_b32_e32 v15, v16
	s_mov_b32 s55, s97
	v_readlane_b32 s77, v253, 51
	v_readlane_b32 s78, v253, 52
	v_readlane_b32 s79, v253, 53
	v_readlane_b32 s80, v253, 54
	v_readlane_b32 s81, v253, 55
	v_readlane_b32 s82, v253, 56
	v_readlane_b32 s83, v253, 57
	v_readlane_b32 s84, v253, 58
	v_readlane_b32 s85, v253, 59
	s_mov_b64 s[58:59], s[90:91]
	s_branch .LBB0_759
.LBB0_757:
	global_load_dwordx4 v[232:235], v248, s[98:99]
	global_load_dwordx4 v[236:239], v248, s[98:99] offset:1024
	global_load_dwordx4 v[240:243], v248, s[98:99] offset:2048
	global_load_dwordx4 v[244:247], v248, s[98:99] offset:3072
	s_add_u32 s98, s98, 0x4000
	s_addc_u32 s99, s99, 0

.LBB0_759:
	s_add_i32 s20, s20, 64
	s_lshl_b32 s0, s17, 15
	v_add_u32_e32 v180, s0, v143
	v_or_b32_e32 v181, s0, v144
	s_setprio 1
	v_add_u32_e32 v182, v180, v112
	ds_read_b128 v[152:155], v182
	v_add_u32_e32 v168, v181, v112
	ds_read_b128 v[156:159], v168 offset:16384
	ds_read_b128 v[160:163], v168 offset:18432
	ds_read_b128 v[164:167], v168 offset:20480
	ds_read_b128 v[168:171], v168 offset:22528
	ds_read_b128 v[172:175], v182 offset:2048
	ds_read_b128 v[176:179], v182 offset:4096
	v_add_u32_e32 v180, v180, v145
	s_waitcnt lgkmcnt(5)
	v_mfma_f32_16x16x32_bf16 v[60:63], v[152:155], v[156:159], v[60:63]
	s_waitcnt lgkmcnt(4)
	v_mfma_f32_16x16x32_bf16 v[56:59], v[152:155], v[160:163], v[56:59]
	s_waitcnt lgkmcnt(3)
	v_mfma_f32_16x16x32_bf16 v[52:55], v[152:155], v[164:167], v[52:55]
	s_waitcnt lgkmcnt(2)
	v_mfma_f32_16x16x32_bf16 v[48:51], v[152:155], v[168:171], v[48:51]
	ds_read_b128 v[152:155], v182 offset:6144
	s_waitcnt lgkmcnt(2)
	v_mfma_f32_16x16x32_bf16 v[44:47], v[172:175], v[156:159], v[44:47]
	v_mfma_f32_16x16x32_bf16 v[40:43], v[172:175], v[160:163], v[40:43]
	v_mfma_f32_16x16x32_bf16 v[36:39], v[172:175], v[164:167], v[36:39]
	v_mfma_f32_16x16x32_bf16 v[32:35], v[172:175], v[168:171], v[32:35]
	s_waitcnt lgkmcnt(1)
	v_mfma_f32_16x16x32_bf16 v[28:31], v[176:179], v[156:159], v[28:31]
	v_mfma_f32_16x16x32_bf16 v[24:27], v[176:179], v[160:163], v[24:27]
	v_mfma_f32_16x16x32_bf16 v[20:23], v[176:179], v[164:167], v[20:23]
	v_mfma_f32_16x16x32_bf16 v[16:19], v[176:179], v[168:171], v[16:19]
	s_waitcnt lgkmcnt(0)
	v_mfma_f32_16x16x32_bf16 v[8:11], v[152:155], v[156:159], v[8:11]
	v_mfma_f32_16x16x32_bf16 v[4:7], v[152:155], v[160:163], v[4:7]
	v_mfma_f32_16x16x32_bf16 v[0:3], v[152:155], v[164:167], v[0:3]
	v_mfma_f32_16x16x32_bf16 v[12:15], v[152:155], v[168:171], v[12:15]
	ds_read_b128 v[152:155], v180
	v_add_u32_e32 v168, v181, v145
	ds_read_b128 v[156:159], v168 offset:16384
	ds_read_b128 v[160:163], v168 offset:18432
	ds_read_b128 v[164:167], v168 offset:20480
	ds_read_b128 v[168:171], v168 offset:22528
	ds_read_b128 v[172:175], v180 offset:2048
	ds_read_b128 v[176:179], v180 offset:4096
	s_waitcnt lgkmcnt(5)
	v_mfma_f32_16x16x32_bf16 v[60:63], v[152:155], v[156:159], v[60:63]
	s_waitcnt lgkmcnt(4)
	v_mfma_f32_16x16x32_bf16 v[56:59], v[152:155], v[160:163], v[56:59]
	s_waitcnt lgkmcnt(3)
	v_mfma_f32_16x16x32_bf16 v[52:55], v[152:155], v[164:167], v[52:55]
	s_waitcnt lgkmcnt(2)
	v_mfma_f32_16x16x32_bf16 v[48:51], v[152:155], v[168:171], v[48:51]
	ds_read_b128 v[152:155], v180 offset:6144
	s_waitcnt lgkmcnt(2)
	v_mfma_f32_16x16x32_bf16 v[44:47], v[172:175], v[156:159], v[44:47]
	v_mfma_f32_16x16x32_bf16 v[40:43], v[172:175], v[160:163], v[40:43]
	v_mfma_f32_16x16x32_bf16 v[36:39], v[172:175], v[164:167], v[36:39]
	v_mfma_f32_16x16x32_bf16 v[32:35], v[172:175], v[168:171], v[32:35]
	s_waitcnt lgkmcnt(1)
	v_mfma_f32_16x16x32_bf16 v[28:31], v[176:179], v[156:159], v[28:31]
	v_mfma_f32_16x16x32_bf16 v[24:27], v[176:179], v[160:163], v[24:27]
	v_mfma_f32_16x16x32_bf16 v[20:23], v[176:179], v[164:167], v[20:23]
	v_mfma_f32_16x16x32_bf16 v[16:19], v[176:179], v[168:171], v[16:19]
	s_waitcnt lgkmcnt(0)
	v_mfma_f32_16x16x32_bf16 v[8:11], v[152:155], v[156:159], v[8:11]
	v_mfma_f32_16x16x32_bf16 v[4:7], v[152:155], v[160:163], v[4:7]
	v_mfma_f32_16x16x32_bf16 v[0:3], v[152:155], v[164:167], v[0:3]
	v_mfma_f32_16x16x32_bf16 v[12:15], v[152:155], v[168:171], v[12:15]
	s_setprio 0
	s_cmpk_gt_u32 s20, 0x3bf
	s_cselect_b64 s[2:3], -1, 0
	s_and_b64 vcc, exec, s[2:3]
	s_cbranch_vccnz .LBB0_761
	s_lshl_b32 s0, s17, 14
	s_xor_b32 s0, s0, 0x4000
	s_lshl_b32 s0, s0, 1
	v_add_u32_e32 v152, s0, v142
	s_waitcnt vmcnt(7)
	ds_write_b128 v152, v[64:67]
	s_waitcnt vmcnt(6)
	ds_write_b128 v152, v[68:71] offset:4096
	s_waitcnt vmcnt(5)
	ds_write_b128 v152, v[72:75] offset:8192
	s_waitcnt vmcnt(4)
	ds_write_b128 v152, v[76:79] offset:12288
	v_add3_u32 v156, s0, v146, v147
	s_waitcnt vmcnt(3)
	ds_write_b128 v156, v[232:235] offset:16384
	s_waitcnt vmcnt(2)
	ds_write_b128 v156, v[236:239] offset:16512
	v_add3_u32 v156, s0, v148, v149
	s_waitcnt vmcnt(1)
	ds_write_b128 v156, v[240:243] offset:16384
	v_add3_u32 v156, s0, v150, v151
	s_waitcnt vmcnt(0)
	ds_write_b128 v156, v[244:247] offset:16384

.LBB0_1367:
	s_ashr_i32 s0, s55, 31
	s_lshr_b32 s0, s0, 26
	s_add_i32 s4, s55, s0
	s_and_b32 s0, s4, 0xffffffc0
	s_sub_i32 s0, s55, s0
	s_ashr_i32 s1, s0, 31
	v_readlane_b32 s8, v253, 50
	s_lshl_b64 s[2:3], s[0:1], 18
	v_readlane_b32 s10, v253, 52
	v_readlane_b32 s9, v253, 51
	v_readlane_b32 s11, v253, 53
	s_add_u32 s10, s8, s2
	v_readlane_b32 s12, v253, 54
	v_readlane_b32 s13, v253, 55
	v_readlane_b32 s14, v253, 56
	v_readlane_b32 s15, v253, 57
	v_readlane_b32 s16, v253, 58
	v_readlane_b32 s17, v253, 59
	v_readlane_b32 s18, v253, 60
	v_readlane_b32 s19, v253, 61
	v_readlane_b32 s20, v253, 62
	v_readlane_b32 s21, v253, 63
	v_readlane_b32 s22, v255, 0
	v_readlane_b32 s23, v255, 1
	s_addc_u32 s11, s9, s3
	s_lshl_b32 s1, s4, 1
	s_and_b32 s4, s1, 0xffffff80
	v_readlane_b32 s12, v254, 34
	v_mov_b32_e32 v127, v250
	v_lshrrev_b32_e32 v248, 6, v250
	v_and_b32_e32 v249, 63, v250
	v_lshlrev_b32_e32 v248, 12, v248
	v_lshl_or_b32 v248, v249, 4, v248
	s_ashr_i32 s5, s4, 31
	s_lshl_b32 s98, s4, 11
	s_add_u32 s98, s98, 0x580000
	s_add_u32 s98, s100, s98
	s_addc_u32 s99, s101, 0
	v_readlane_b32 s14, v254, 36
	v_readlane_b32 s15, v254, 37
	v_readlane_b32 s26, v254, 48
	v_readlane_b32 s27, v254, 49
	s_movk_i32 s1, 0x4800
	v_and_b32_e32 v64, 31, v127
	v_ashrrev_i32_e32 v65, 5, v127
	s_lshl_b64 s[8:9], s[4:5], 2
	s_mov_b64 s[14:15], s[26:27]
	v_lshlrev_b32_e32 v66, 2, v64
	v_mul_lo_u32 v1, v65, s1
	v_readlane_b32 s13, v254, 35
	s_add_u32 s12, s14, s8
	v_or_b32_e32 v112, v66, v1
	s_addc_u32 s13, s15, s9
	v_lshlrev_b64 v[62:63], 2, v[112:113]
	s_waitcnt vmcnt(1)
	v_lshl_add_u64 v[104:105], s[12:13], 0, v[62:63]
	s_movk_i32 s1, 0x2000
	v_add_co_u32_e32 v20, vcc, s1, v104
	s_movk_i32 s1, 0x4000
	s_nop 0
	v_addc_co_u32_e32 v21, vcc, 0, v105, vcc
	v_add_co_u32_e32 v24, vcc, s1, v104
	s_movk_i32 s1, 0x6000
	s_nop 0
	v_addc_co_u32_e32 v25, vcc, 0, v105, vcc
	v_add_co_u32_e32 v28, vcc, s1, v104
	s_mov_b32 s1, 0x9000
	s_nop 0
	v_addc_co_u32_e32 v29, vcc, 0, v105, vcc
	v_lshlrev_b32_e32 v0, 7, v127
	s_waitcnt vmcnt(0)
	v_add_co_u32_e32 v32, vcc, s1, v104
	v_and_b32_e32 v0, 0xfffffc00, v0
	v_lshlrev_b32_e32 v67, 4, v127
	v_addc_co_u32_e32 v33, vcc, 0, v105, vcc
	s_mov_b32 s1, 0xb000
	v_add_u32_e32 v8, 0x10000, v0
	v_and_b32_e32 v4, 0x70, v67
	v_mov_b32_e32 v5, v113
	v_mov_b32_e32 v9, v113
	v_add_co_u32_e32 v36, vcc, s1, v104
	v_add_u32_e32 v2, 0x8000, v0
	v_add_u32_e32 v10, 0x18000, v0
	v_lshl_add_u64 v[12:13], s[10:11], 0, v[4:5]
	v_mov_b32_e32 v1, v113
	v_mov_b32_e32 v3, v113
	v_lshlrev_b64 v[54:55], 1, v[8:9]
	v_mov_b32_e32 v11, v113
	v_addc_co_u32_e32 v37, vcc, 0, v105, vcc
	s_mov_b32 s1, 0xd000
	v_lshl_add_u64 v[48:49], v[0:1], 1, v[12:13]
	v_lshlrev_b64 v[50:51], 1, v[2:3]
	v_lshl_add_u64 v[56:57], v[12:13], 0, v[54:55]
	v_lshlrev_b64 v[58:59], 1, v[10:11]
	v_add_co_u32_e32 v40, vcc, s1, v104
	v_lshl_add_u64 v[52:53], v[12:13], 0, v[50:51]
	global_load_dwordx4 v[0:3], v[48:49], off
	global_load_dwordx4 v[4:7], v[52:53], off
	v_lshl_add_u64 v[60:61], v[12:13], 0, v[58:59]
	global_load_dwordx4 v[8:11], v[56:57], off
	global_load_dwordx4 v[12:15], v[60:61], off
	v_addc_co_u32_e32 v41, vcc, 0, v105, vcc
	s_mov_b32 s1, 0xf000
	v_add_co_u32_e32 v44, vcc, s1, v104
	global_load_dwordx4 v[232:235], v248, s[98:99]
	global_load_dwordx4 v[236:239], v248, s[98:99] offset:1024
	global_load_dwordx4 v[240:243], v248, s[98:99] offset:2048
	global_load_dwordx4 v[244:247], v248, s[98:99] offset:3072
	s_add_u32 s98, s98, 0x4000
	s_addc_u32 s99, s99, 0
	s_nop 0
	v_addc_co_u32_e32 v45, vcc, 0, v105, vcc
	s_nop 0
	s_nop 0
	s_nop 0
	s_nop 0
	s_nop 0
	v_lshrrev_b32_e32 v112, 4, v127
	v_xor_b32_e32 v68, v112, v127
	v_lshlrev_b32_e32 v68, 4, v68
	v_and_b32_e32 v67, 0xffffff80, v67
	s_movk_i32 s1, 0x70
	v_and_or_b32 v130, v68, s1, v67
	s_waitcnt vmcnt(7)
	ds_write_b128 v130, v[0:3]
	s_waitcnt vmcnt(6)
	ds_write_b128 v130, v[4:7] offset:4096
	s_waitcnt vmcnt(5)
	ds_write_b128 v130, v[8:11] offset:8192
	s_waitcnt vmcnt(4)
	ds_write_b128 v130, v[12:15] offset:12288
	v_lshlrev_b32_e32 v5, 1, v127
	v_bitop3_b32 v5, v5, v65, 6 bitop3:0x6c
	v_lshlrev_b32_e32 v6, 3, v5
	v_lshlrev_b32_e32 v5, 4, v5
	v_lshl_add_u32 v5, v64, 9, v5
	s_mov_b32 s1, 0x90000
	v_lshlrev_b32_e32 v4, 8, v64
	s_waitcnt vmcnt(3)
	ds_write_b128 v5, v[232:235] offset:16384
	s_waitcnt vmcnt(2)
	ds_write_b128 v5, v[236:239] offset:16512
	v_or_b32_e32 v5, 2, v66
	v_lshrrev_b32_e32 v8, 1, v5
	v_bitop3_b32 v8, v8, v65, 7 bitop3:0x6c
	v_lshlrev_b32_e32 v9, 3, v8
	v_lshlrev_b32_e32 v8, 4, v8
	v_lshlrev_b32_e32 v7, 6, v5
	v_lshl_add_u32 v5, v5, 7, v8
	s_waitcnt vmcnt(1)
	ds_write_b128 v5, v[240:243] offset:16384
	v_or_b32_e32 v5, 3, v66
	v_lshrrev_b32_e32 v10, 1, v5
	v_bitop3_b32 v10, v10, v65, 7 bitop3:0x6c
	v_lshlrev_b32_e32 v11, 3, v10
	v_lshlrev_b32_e32 v10, 4, v10
	v_lshlrev_b32_e32 v8, 6, v5
	v_lshl_add_u32 v5, v5, 7, v10
	s_waitcnt vmcnt(0)
	ds_write_b128 v5, v[244:247] offset:16384
	v_add_co_u32_e32 v0, vcc, s1, v104
	s_mov_b32 s1, 0x92000
	s_nop 0
	v_addc_co_u32_e32 v1, vcc, 0, v105, vcc
	v_add_co_u32_e32 v2, vcc, s1, v104
	s_mov_b32 s1, 0x94000
	s_nop 0
	v_addc_co_u32_e32 v3, vcc, 0, v105, vcc
	s_waitcnt lgkmcnt(0)
	s_barrier
	global_load_dwordx4 v[64:67], v[48:49], off offset:128
	global_load_dwordx4 v[68:71], v[52:53], off offset:128
	global_load_dwordx4 v[72:75], v[56:57], off offset:128
	global_load_dwordx4 v[76:79], v[60:61], off offset:128
	global_load_dwordx4 v[232:235], v248, s[98:99]
	global_load_dwordx4 v[236:239], v248, s[98:99] offset:1024
	global_load_dwordx4 v[240:243], v248, s[98:99] offset:2048
	global_load_dwordx4 v[244:247], v248, s[98:99] offset:3072
	s_add_u32 s98, s98, 0x4000
	s_addc_u32 s99, s99, 0
	v_add_co_u32_e32 v0, vcc, s1, v104
	s_mov_b32 s1, 0x96000
	s_nop 0
	v_addc_co_u32_e32 v1, vcc, 0, v105, vcc
	v_add_co_u32_e32 v2, vcc, s1, v104
	s_mov_b32 s1, 0x99000
	s_nop 0
	v_addc_co_u32_e32 v3, vcc, 0, v105, vcc
	v_add_co_u32_e32 v0, vcc, s1, v104
	s_mov_b32 s1, 0x9b000
	s_nop 0
	v_addc_co_u32_e32 v1, vcc, 0, v105, vcc
	v_add_co_u32_e32 v2, vcc, s1, v104
	s_mov_b32 s1, 0x9d000
	s_nop 0
	v_addc_co_u32_e32 v3, vcc, 0, v105, vcc
	v_add_co_u32_e32 v0, vcc, s1, v104
	s_mov_b32 s1, 0x9f000
	s_nop 0
	v_addc_co_u32_e32 v1, vcc, 0, v105, vcc
	v_add_co_u32_e32 v2, vcc, s1, v104
	v_and_b32_e32 v126, 15, v127
	s_nop 0
	v_addc_co_u32_e32 v3, vcc, 0, v105, vcc
	v_bfe_u32 v129, v127, 6, 1
	v_ashrrev_i32_e32 v128, 7, v127
	v_lshlrev_b32_e32 v0, 7, v126
	v_bfe_u32 v114, v127, 4, 2
	v_lshl_or_b32 v131, v128, 13, v0
	v_lshl_or_b32 v132, v129, 13, v0
	v_bfe_u32 v0, v127, 1, 3
	v_bitop3_b32 v1, v112, v0, 3 bitop3:0x6c
	v_bitop3_b32 v0, v114, v0, 4 bitop3:0x36
	v_lshlrev_b32_e32 v3, 3, v0
	v_and_b32_e32 v0, 7, v127
	v_lshlrev_b32_e32 v2, 3, v1
	v_lshlrev_b32_e32 v112, 4, v0
	v_bfe_u32 v0, v127, 3, 22
	v_mov_b32_e32 v1, v113
	s_add_u32 s2, s33, s2
	v_lshlrev_b64 v[0:1], 11, v[0:1]
	s_addc_u32 s3, s34, s3
	v_lshl_add_u64 v[114:115], s[2:3], 0, v[0:1]
	v_lshl_add_u64 v[116:117], s[2:3], 0, v[50:51]
	v_lshl_add_u64 v[118:119], s[2:3], 0, v[54:55]
	v_lshl_add_u64 v[120:121], s[2:3], 0, v[58:59]
	s_add_u32 s2, s35, s8
	s_addc_u32 s3, s36, s9
	v_lshl_add_u64 v[122:123], s[2:3], 0, v[62:63]
	v_lshlrev_b32_e32 v133, 1, v2
	v_lshlrev_b32_e32 v134, 1, v3
	v_lshlrev_b32_e32 v135, 1, v4
	v_lshlrev_b32_e32 v136, 1, v6
	v_lshlrev_b32_e32 v137, 1, v7
	v_lshlrev_b32_e32 v138, 1, v9
	v_lshlrev_b32_e32 v139, 1, v8
	v_lshlrev_b32_e32 v140, 1, v11
	s_mov_b32 s1, 0
	s_mov_b32 s5, 0
	v_mov_b32_e32 v16, v113
	v_mov_b32_e32 v17, v113
	v_mov_b32_e32 v18, v113
	v_mov_b32_e32 v19, v113
	v_mov_b32_e32 v20, v113
	v_mov_b32_e32 v21, v113
	v_mov_b32_e32 v22, v113
	v_mov_b32_e32 v23, v113
	v_mov_b32_e32 v24, v113
	v_mov_b32_e32 v25, v113
	v_mov_b32_e32 v26, v113
	v_mov_b32_e32 v27, v113
	v_mov_b32_e32 v28, v113
	v_mov_b32_e32 v29, v113
	v_mov_b32_e32 v30, v113
	v_mov_b32_e32 v31, v113
	v_mov_b32_e32 v32, v113
	v_mov_b32_e32 v33, v113
	v_mov_b32_e32 v34, v113
	v_mov_b32_e32 v35, v113
	v_mov_b32_e32 v36, v113
	v_mov_b32_e32 v37, v113
	v_mov_b32_e32 v38, v113
	v_mov_b32_e32 v39, v113
	v_mov_b32_e32 v40, v113
	v_mov_b32_e32 v41, v113
	v_mov_b32_e32 v42, v113
	v_mov_b32_e32 v43, v113
	v_mov_b32_e32 v44, v113
	v_mov_b32_e32 v45, v113
	v_mov_b32_e32 v46, v113
	v_mov_b32_e32 v47, v113
	v_mov_b32_e32 v48, v113
	v_mov_b32_e32 v49, v113
	v_mov_b32_e32 v50, v113
	v_mov_b32_e32 v51, v113
	v_mov_b32_e32 v52, v113
	v_mov_b32_e32 v53, v113
	v_mov_b32_e32 v54, v113
	v_mov_b32_e32 v55, v113
	v_mov_b32_e32 v56, v113
	v_mov_b32_e32 v57, v113
	v_mov_b32_e32 v58, v113
	v_mov_b32_e32 v59, v113
	v_mov_b32_e32 v60, v113
	v_mov_b32_e32 v61, v113
	v_mov_b32_e32 v62, v113
	v_mov_b32_e32 v63, v113
	v_mov_b32_e32 v12, v113
	v_mov_b32_e32 v13, v113
	v_mov_b32_e32 v14, v113
	v_mov_b32_e32 v15, v113
	v_mov_b32_e32 v8, v113
	v_mov_b32_e32 v9, v113
	v_mov_b32_e32 v10, v113
	v_mov_b32_e32 v11, v113
	v_mov_b32_e32 v4, v113
	v_mov_b32_e32 v5, v113
	v_mov_b32_e32 v6, v113
	v_mov_b32_e32 v7, v113
	v_mov_b32_e32 v0, v113
	v_mov_b32_e32 v1, v113
	v_mov_b32_e32 v2, v113
	v_mov_b32_e32 v3, v113
	v_readlane_b32 s16, v254, 38
	v_readlane_b32 s17, v254, 39
	v_readlane_b32 s18, v254, 40
	v_readlane_b32 s19, v254, 41
	v_readlane_b32 s20, v254, 42
	v_readlane_b32 s21, v254, 43
	v_readlane_b32 s22, v254, 44
	v_readlane_b32 s23, v254, 45
	v_readlane_b32 s24, v254, 46
	v_readlane_b32 s25, v254, 47
	s_branch .LBB0_1369

.LBB0_1369:
	s_lshl_b32 s2, s5, 15
	v_add_u32_e32 v141, s2, v131
	v_or_b32_e32 v170, s2, v132
	s_setprio 1
	v_add_u32_e32 v171, v141, v133
	ds_read_b128 v[142:145], v171
	v_add_u32_e32 v158, v170, v133
	ds_read_b128 v[146:149], v158 offset:16384
	ds_read_b128 v[150:153], v158 offset:18432
	ds_read_b128 v[154:157], v158 offset:20480
	ds_read_b128 v[158:161], v158 offset:22528
	ds_read_b128 v[162:165], v171 offset:2048
	ds_read_b128 v[166:169], v171 offset:4096
	v_add_u32_e32 v141, v141, v134
	s_waitcnt lgkmcnt(5)
	v_mfma_f32_16x16x32_bf16 v[60:63], v[142:145], v[146:149], v[60:63]
	s_waitcnt lgkmcnt(4)
	v_mfma_f32_16x16x32_bf16 v[56:59], v[142:145], v[150:153], v[56:59]
	s_waitcnt lgkmcnt(3)
	v_mfma_f32_16x16x32_bf16 v[52:55], v[142:145], v[154:157], v[52:55]
	s_waitcnt lgkmcnt(2)
	v_mfma_f32_16x16x32_bf16 v[48:51], v[142:145], v[158:161], v[48:51]
	ds_read_b128 v[142:145], v171 offset:6144
	s_waitcnt lgkmcnt(2)
	v_mfma_f32_16x16x32_bf16 v[44:47], v[162:165], v[146:149], v[44:47]
	v_mfma_f32_16x16x32_bf16 v[40:43], v[162:165], v[150:153], v[40:43]
	v_mfma_f32_16x16x32_bf16 v[36:39], v[162:165], v[154:157], v[36:39]
	v_mfma_f32_16x16x32_bf16 v[32:35], v[162:165], v[158:161], v[32:35]
	s_waitcnt lgkmcnt(1)
	v_mfma_f32_16x16x32_bf16 v[28:31], v[166:169], v[146:149], v[28:31]
	v_mfma_f32_16x16x32_bf16 v[24:27], v[166:169], v[150:153], v[24:27]
	v_mfma_f32_16x16x32_bf16 v[20:23], v[166:169], v[154:157], v[20:23]
	v_mfma_f32_16x16x32_bf16 v[16:19], v[166:169], v[158:161], v[16:19]
	s_waitcnt lgkmcnt(0)
	v_mfma_f32_16x16x32_bf16 v[12:15], v[142:145], v[146:149], v[12:15]
	v_mfma_f32_16x16x32_bf16 v[8:11], v[142:145], v[150:153], v[8:11]
	v_mfma_f32_16x16x32_bf16 v[4:7], v[142:145], v[154:157], v[4:7]
	v_mfma_f32_16x16x32_bf16 v[0:3], v[142:145], v[158:161], v[0:3]
	ds_read_b128 v[142:145], v141
	v_add_u32_e32 v158, v170, v134
	ds_read_b128 v[146:149], v158 offset:16384
	ds_read_b128 v[150:153], v158 offset:18432
	ds_read_b128 v[154:157], v158 offset:20480
	ds_read_b128 v[158:161], v158 offset:22528
	ds_read_b128 v[162:165], v141 offset:2048
	ds_read_b128 v[166:169], v141 offset:4096
	s_waitcnt lgkmcnt(5)
	v_mfma_f32_16x16x32_bf16 v[60:63], v[142:145], v[146:149], v[60:63]
	s_waitcnt lgkmcnt(4)
	v_mfma_f32_16x16x32_bf16 v[56:59], v[142:145], v[150:153], v[56:59]
	s_waitcnt lgkmcnt(3)
	v_mfma_f32_16x16x32_bf16 v[52:55], v[142:145], v[154:157], v[52:55]
	s_waitcnt lgkmcnt(2)
	v_mfma_f32_16x16x32_bf16 v[48:51], v[142:145], v[158:161], v[48:51]
	ds_read_b128 v[142:145], v141 offset:6144
	s_waitcnt lgkmcnt(2)
	v_mfma_f32_16x16x32_bf16 v[44:47], v[162:165], v[146:149], v[44:47]
	v_mfma_f32_16x16x32_bf16 v[40:43], v[162:165], v[150:153], v[40:43]
	v_mfma_f32_16x16x32_bf16 v[36:39], v[162:165], v[154:157], v[36:39]
	v_mfma_f32_16x16x32_bf16 v[32:35], v[162:165], v[158:161], v[32:35]
	s_waitcnt lgkmcnt(1)
	v_mfma_f32_16x16x32_bf16 v[28:31], v[166:169], v[146:149], v[28:31]
	v_mfma_f32_16x16x32_bf16 v[24:27], v[166:169], v[150:153], v[24:27]
	v_mfma_f32_16x16x32_bf16 v[20:23], v[166:169], v[154:157], v[20:23]
	v_mfma_f32_16x16x32_bf16 v[16:19], v[166:169], v[158:161], v[16:19]
	s_waitcnt lgkmcnt(0)
	v_mfma_f32_16x16x32_bf16 v[12:15], v[142:145], v[146:149], v[12:15]
	v_mfma_f32_16x16x32_bf16 v[8:11], v[142:145], v[150:153], v[8:11]
	v_mfma_f32_16x16x32_bf16 v[4:7], v[142:145], v[154:157], v[4:7]
	v_mfma_f32_16x16x32_bf16 v[0:3], v[142:145], v[158:161], v[0:3]
	s_setprio 0
	s_cmpk_gt_u32 s1, 0x3bf
	s_cselect_b64 s[2:3], -1, 0
	s_and_b64 vcc, exec, s[2:3]
	s_cbranch_vccnz .LBB0_1371
	s_lshl_b32 s8, s5, 14
	s_xor_b32 s8, s8, 0x4000
	s_lshl_b32 s8, s8, 1
	v_add_u32_e32 v141, s8, v130
	s_waitcnt vmcnt(7)
	ds_write_b128 v141, v[64:67]
	s_waitcnt vmcnt(6)
	ds_write_b128 v141, v[68:71] offset:4096
	s_waitcnt vmcnt(5)
	ds_write_b128 v141, v[72:75] offset:8192
	s_waitcnt vmcnt(4)
	ds_write_b128 v141, v[76:79] offset:12288
	v_add3_u32 v141, s8, v135, v136
	s_waitcnt vmcnt(3)
	ds_write_b128 v141, v[232:235] offset:16384
	s_waitcnt vmcnt(2)
	ds_write_b128 v141, v[236:239] offset:16512
	v_add3_u32 v141, s8, v137, v138
	s_waitcnt vmcnt(1)
	ds_write_b128 v141, v[240:243] offset:16384
	v_add3_u32 v141, s8, v139, v140
	s_waitcnt vmcnt(0)
	ds_write_b128 v141, v[244:247] offset:16384
.LBB0_1371:
	s_cmpk_gt_u32 s1, 0x37f
	s_cbranch_scc1 .LBB0_1368
	v_lshl_add_u64 v[64:65], v[114:115], 0, v[112:113]
	v_lshl_add_u64 v[68:69], v[116:117], 0, v[112:113]
	v_lshl_add_u64 v[72:73], v[118:119], 0, v[112:113]
	v_lshl_add_u64 v[76:77], v[120:121], 0, v[112:113]
	global_load_dwordx4 v[64:67], v[64:65], off
	global_load_dwordx4 v[68:71], v[68:69], off
	global_load_dwordx4 v[72:75], v[72:73], off
	global_load_dwordx4 v[76:79], v[76:77], off
	global_load_dwordx4 v[232:235], v248, s[98:99]
	global_load_dwordx4 v[236:239], v248, s[98:99] offset:1024
	global_load_dwordx4 v[240:243], v248, s[98:99] offset:2048
	global_load_dwordx4 v[244:247], v248, s[98:99] offset:3072
	s_add_u32 s98, s98, 0x4000
	s_addc_u32 s99, s99, 0
	s_branch .LBB0_1368

.LBB0_1805:
	s_ashr_i32 s2, s29, 31
	s_lshr_b32 s2, s2, 26
	s_add_i32 s2, s29, s2
	s_and_b32 s3, s2, 0xffffffc0
	s_lshl_b32 s2, s2, 1
	s_and_b32 s8, s2, 0xffffff80
	v_readlane_b32 s76, v254, 50
	v_mov_b32_e32 v124, v250
	v_lshrrev_b32_e32 v248, 6, v250
	v_and_b32_e32 v249, 63, v250
	v_lshlrev_b32_e32 v248, 12, v248
	v_lshl_or_b32 v248, v249, 4, v248
	s_ashr_i32 s9, s8, 31
	s_lshl_b32 s98, s8, 11
	s_add_u32 s98, s98, 0xa00000
	s_add_u32 s98, s100, s98
	s_addc_u32 s99, s101, 0
	v_readlane_b32 s78, v254, 52
	v_readlane_b32 s79, v254, 53
	v_readlane_b32 s82, v254, 56
	v_readlane_b32 s83, v254, 57
	s_sub_i32 s30, s29, s3
	v_and_b32_e32 v48, 31, v124
	s_lshl_b64 s[2:3], s[8:9], 2
	s_mov_b64 s[78:79], s[82:83]
	v_ashrrev_i32_e32 v64, 5, v124
	v_lshlrev_b32_e32 v65, 2, v48
	s_add_u32 s34, s78, s2
	v_lshl_or_b32 v112, v64, 13, v65
	s_addc_u32 s35, s79, s3
	v_lshlrev_b64 v[62:63], 2, v[112:113]
	s_waitcnt vmcnt(1)
	v_lshl_add_u64 v[104:105], s[34:35], 0, v[62:63]
	v_add_co_u32_e32 v16, vcc, s21, v104
	s_lshl_b32 s14, s30, 7
	s_nop 0
	v_addc_co_u32_e32 v17, vcc, 0, v105, vcc
	s_ashr_i32 s15, s14, 31
	v_add_co_u32_e32 v24, vcc, s22, v104
	s_lshl_b64 s[12:13], s[14:15], 10
	s_lshl_b64 s[10:11], s[14:15], 11
	v_lshlrev_b32_e32 v0, 7, v124
	v_addc_co_u32_e32 v25, vcc, 0, v105, vcc
	s_add_u32 s36, s48, s10
	v_and_b32_e32 v0, 0xfffffc00, v0
	v_lshlrev_b32_e32 v49, 4, v124
	s_waitcnt vmcnt(0)
	v_add_co_u32_e32 v32, vcc, s23, v104
	s_addc_u32 s37, s49, s11
	v_add_u32_e32 v8, 0x10000, v0
	v_and_b32_e32 v4, 0x70, v49
	v_mov_b32_e32 v5, v113
	v_mov_b32_e32 v9, v113
	v_addc_co_u32_e32 v33, vcc, 0, v105, vcc
	v_add_u32_e32 v2, 0x8000, v0
	v_add_u32_e32 v40, 0x18000, v0
	v_lshl_add_u64 v[42:43], s[36:37], 0, v[4:5]
	v_mov_b32_e32 v1, v113
	v_mov_b32_e32 v3, v113
	v_lshlrev_b64 v[58:59], 1, v[8:9]
	v_mov_b32_e32 v41, v113
	v_add_co_u32_e32 v36, vcc, s24, v104
	v_lshl_add_u64 v[52:53], v[0:1], 1, v[42:43]
	v_lshlrev_b64 v[54:55], 1, v[2:3]
	v_lshl_add_u64 v[60:61], v[42:43], 0, v[58:59]
	v_addc_co_u32_e32 v37, vcc, 0, v105, vcc
	v_lshlrev_b64 v[120:121], 1, v[40:41]
	v_lshl_add_u64 v[56:57], v[42:43], 0, v[54:55]
	global_load_dwordx4 v[0:3], v[52:53], off
	global_load_dwordx4 v[4:7], v[56:57], off
	s_nop 0
	s_nop 0
	s_nop 0
	s_nop 0
	s_nop 0
	v_lshl_add_u64 v[76:77], v[42:43], 0, v[120:121]
	s_nop 0
	global_load_dwordx4 v[40:43], v[60:61], off
	global_load_dwordx4 v[44:47], v[76:77], off
	global_load_dwordx4 v[232:235], v248, s[98:99]
	global_load_dwordx4 v[236:239], v248, s[98:99] offset:1024
	global_load_dwordx4 v[240:243], v248, s[98:99] offset:2048
	global_load_dwordx4 v[244:247], v248, s[98:99] offset:3072
	s_add_u32 s98, s98, 0x4000
	s_addc_u32 s99, s99, 0
	v_lshrrev_b32_e32 v112, 4, v124
	v_lshlrev_b32_e32 v50, 1, v124
	v_xor_b32_e32 v51, v112, v124
	v_and_b32_e32 v49, 0xffffff80, v49
	v_bitop3_b32 v50, v50, v64, 6 bitop3:0x6c
	v_lshlrev_b32_e32 v51, 4, v51
	v_lshlrev_b32_e32 v134, 3, v50
	v_lshlrev_b32_e32 v50, 4, v50
	v_and_or_b32 v128, v51, s20, v49
	v_lshlrev_b32_e32 v133, 8, v48
	v_lshl_add_u32 v66, v48, 9, v50
	v_and_b32_e32 v127, 15, v124
	v_bfe_u32 v126, v124, 6, 1
	v_ashrrev_i32_e32 v125, 7, v124
	v_bfe_u32 v114, v124, 4, 2
	s_add_u32 s10, s16, s10
	s_addc_u32 s11, s17, s11
	s_add_u32 s2, s18, s2
	s_addc_u32 s3, s19, s3
	v_lshl_add_u64 v[116:117], s[10:11], 0, v[54:55]
	v_lshl_add_u64 v[118:119], s[10:11], 0, v[58:59]
	v_lshl_add_u64 v[120:121], s[10:11], 0, v[120:121]
	v_lshl_add_u64 v[122:123], s[2:3], 0, v[62:63]
	v_lshlrev_b32_e32 v133, 1, v133
	v_lshlrev_b32_e32 v134, 1, v134
	s_mov_b32 s9, 0
	v_mov_b32_e32 v54, v113
	v_mov_b32_e32 v55, v113
	v_mov_b32_e32 v58, v113
	v_mov_b32_e32 v59, v113
	v_mov_b32_e32 v62, v113
	v_mov_b32_e32 v63, v113
	v_readlane_b32 s77, v254, 51
	v_readlane_b32 s80, v254, 54
	v_readlane_b32 s81, v254, 55
	v_readlane_b32 s84, v254, 58
	v_readlane_b32 s85, v254, 59
	v_readlane_b32 s86, v254, 60
	v_readlane_b32 s87, v254, 61
	v_readlane_b32 s88, v254, 62
	v_readlane_b32 s89, v254, 63
	v_readlane_b32 s90, v253, 0
	v_readlane_b32 s91, v253, 1
	v_mov_b32_e32 v16, v113
	v_mov_b32_e32 v20, v113
	s_waitcnt vmcnt(6)
	ds_write_b128 v128, v[0:3]
	ds_write_b128 v128, v[4:7] offset:4096
	s_waitcnt vmcnt(5)
	ds_write_b128 v128, v[40:43] offset:8192
	s_waitcnt vmcnt(4)
	ds_write_b128 v128, v[44:47] offset:12288
	s_waitcnt vmcnt(3)
	ds_write_b128 v66, v[232:235] offset:16384
	v_or_b32_e32 v4, 2, v65
	v_lshrrev_b32_e32 v6, 1, v4
	v_bitop3_b32 v6, v6, v64, 7 bitop3:0x6c
	v_lshlrev_b32_e32 v7, 3, v6
	v_lshlrev_b32_e32 v6, 4, v6
	s_waitcnt vmcnt(2)
	ds_write_b128 v66, v[236:239] offset:16512
	v_lshlrev_b32_e32 v5, 6, v4
	v_lshl_add_u32 v4, v4, 7, v6
	s_waitcnt vmcnt(1)
	ds_write_b128 v4, v[240:243] offset:16384
	v_or_b32_e32 v4, 3, v65
	v_lshrrev_b32_e32 v8, 1, v4
	v_bitop3_b32 v8, v8, v64, 7 bitop3:0x6c
	v_lshlrev_b32_e32 v9, 3, v8
	v_lshlrev_b32_e32 v8, 4, v8
	v_lshlrev_b32_e32 v6, 6, v4
	v_lshl_add_u32 v4, v4, 7, v8
	s_waitcnt vmcnt(0)
	ds_write_b128 v4, v[244:247] offset:16384
	v_add_co_u32_e32 v0, vcc, s25, v104
	s_waitcnt lgkmcnt(0)
	s_nop 0
	v_addc_co_u32_e32 v1, vcc, 0, v105, vcc
	s_barrier
	global_load_dwordx4 v[64:67], v[52:53], off offset:128
	global_load_dwordx4 v[68:71], v[56:57], off offset:128
	global_load_dwordx4 v[72:75], v[60:61], off offset:128
	s_nop 0
	global_load_dwordx4 v[76:79], v[76:77], off offset:128
	global_load_dwordx4 v[232:235], v248, s[98:99]
	global_load_dwordx4 v[236:239], v248, s[98:99] offset:1024
	global_load_dwordx4 v[240:243], v248, s[98:99] offset:2048
	global_load_dwordx4 v[244:247], v248, s[98:99] offset:3072
	s_add_u32 s98, s98, 0x4000
	s_addc_u32 s99, s99, 0
	s_nop 0
	v_add_co_u32_e32 v0, vcc, s26, v104
	v_lshlrev_b32_e32 v135, 1, v5
	s_nop 0
	v_addc_co_u32_e32 v1, vcc, 0, v105, vcc
	v_add_co_u32_e32 v0, vcc, s27, v104
	v_lshlrev_b32_e32 v136, 1, v7
	s_nop 0
	v_addc_co_u32_e32 v1, vcc, 0, v105, vcc
	v_add_co_u32_e32 v0, vcc, s28, v104
	v_lshlrev_b32_e32 v137, 1, v6
	s_nop 0
	v_addc_co_u32_e32 v1, vcc, 0, v105, vcc
	v_lshlrev_b32_e32 v0, 7, v127
	v_lshl_or_b32 v129, v125, 13, v0
	v_lshl_or_b32 v130, v126, 13, v0
	v_bfe_u32 v0, v124, 1, 3
	v_bitop3_b32 v1, v112, v0, 3 bitop3:0x6c
	v_bitop3_b32 v0, v114, v0, 4 bitop3:0x36
	v_lshlrev_b32_e32 v3, 3, v0
	v_and_b32_e32 v0, 7, v124
	v_lshlrev_b32_e32 v2, 3, v1
	v_lshlrev_b32_e32 v112, 4, v0
	v_bfe_u32 v0, v124, 3, 22
	v_mov_b32_e32 v1, v113
	v_lshlrev_b64 v[0:1], 11, v[0:1]
	v_lshl_add_u64 v[114:115], s[10:11], 0, v[0:1]
	v_lshlrev_b32_e32 v131, 1, v2
	v_lshlrev_b32_e32 v132, 1, v3
	v_lshlrev_b32_e32 v138, 1, v9
	s_mov_b32 s10, 0
	v_mov_b32_e32 v17, v113
	v_mov_b32_e32 v18, v113
	v_mov_b32_e32 v19, v113
	v_mov_b32_e32 v21, v113
	v_mov_b32_e32 v22, v113
	v_mov_b32_e32 v23, v113
	v_mov_b32_e32 v24, v113
	v_mov_b32_e32 v25, v113
	v_mov_b32_e32 v26, v113
	v_mov_b32_e32 v27, v113
	v_mov_b32_e32 v28, v113
	v_mov_b32_e32 v29, v113
	v_mov_b32_e32 v30, v113
	v_mov_b32_e32 v31, v113
	v_mov_b32_e32 v32, v113
	v_mov_b32_e32 v33, v113
	v_mov_b32_e32 v34, v113
	v_mov_b32_e32 v35, v113
	v_mov_b32_e32 v36, v113
	v_mov_b32_e32 v37, v113
	v_mov_b32_e32 v38, v113
	v_mov_b32_e32 v39, v113
	v_mov_b32_e32 v40, v113
	v_mov_b32_e32 v41, v113
	v_mov_b32_e32 v42, v113
	v_mov_b32_e32 v43, v113
	v_mov_b32_e32 v44, v113
	v_mov_b32_e32 v45, v113
	v_mov_b32_e32 v46, v113
	v_mov_b32_e32 v47, v113
	v_mov_b32_e32 v48, v113
	v_mov_b32_e32 v49, v113
	v_mov_b32_e32 v50, v113
	v_mov_b32_e32 v51, v113
	v_mov_b32_e32 v52, v113
	v_mov_b32_e32 v53, v113
	v_mov_b32_e32 v56, v113
	v_mov_b32_e32 v57, v113
	v_mov_b32_e32 v60, v113
	v_mov_b32_e32 v61, v113
	v_mov_b32_e32 v8, v113
	v_mov_b32_e32 v9, v113
	v_mov_b32_e32 v10, v113
	v_mov_b32_e32 v11, v113
	v_mov_b32_e32 v4, v113
	v_mov_b32_e32 v5, v113
	v_mov_b32_e32 v6, v113
	v_mov_b32_e32 v7, v113
	v_mov_b32_e32 v0, v113
	v_mov_b32_e32 v1, v113
	v_mov_b32_e32 v2, v113
	v_mov_b32_e32 v3, v113
	v_mov_b32_e32 v12, v113
	v_mov_b32_e32 v13, v113
	v_mov_b32_e32 v14, v113
	v_mov_b32_e32 v15, v113
	s_branch .LBB0_1807

.LBB0_1807:
	s_lshl_b32 s2, s10, 15
	v_add_u32_e32 v139, s2, v129
	v_or_b32_e32 v168, s2, v130
	s_setprio 1
	v_add_u32_e32 v169, v139, v131
	ds_read_b128 v[140:143], v169
	v_add_u32_e32 v156, v168, v131
	ds_read_b128 v[144:147], v156 offset:16384
	ds_read_b128 v[148:151], v156 offset:18432
	ds_read_b128 v[152:155], v156 offset:20480
	ds_read_b128 v[156:159], v156 offset:22528
	ds_read_b128 v[160:163], v169 offset:2048
	ds_read_b128 v[164:167], v169 offset:4096
	v_add_u32_e32 v139, v139, v132
	s_waitcnt lgkmcnt(5)
	v_mfma_f32_16x16x32_bf16 v[60:63], v[140:143], v[144:147], v[60:63]
	s_waitcnt lgkmcnt(4)
	v_mfma_f32_16x16x32_bf16 v[56:59], v[140:143], v[148:151], v[56:59]
	s_waitcnt lgkmcnt(3)
	v_mfma_f32_16x16x32_bf16 v[52:55], v[140:143], v[152:155], v[52:55]
	s_waitcnt lgkmcnt(2)
	v_mfma_f32_16x16x32_bf16 v[48:51], v[140:143], v[156:159], v[48:51]
	ds_read_b128 v[140:143], v169 offset:6144
	s_waitcnt lgkmcnt(2)
	v_mfma_f32_16x16x32_bf16 v[44:47], v[160:163], v[144:147], v[44:47]
	v_mfma_f32_16x16x32_bf16 v[40:43], v[160:163], v[148:151], v[40:43]
	v_mfma_f32_16x16x32_bf16 v[36:39], v[160:163], v[152:155], v[36:39]
	v_mfma_f32_16x16x32_bf16 v[32:35], v[160:163], v[156:159], v[32:35]
	s_waitcnt lgkmcnt(1)
	v_mfma_f32_16x16x32_bf16 v[28:31], v[164:167], v[144:147], v[28:31]
	v_mfma_f32_16x16x32_bf16 v[24:27], v[164:167], v[148:151], v[24:27]
	v_mfma_f32_16x16x32_bf16 v[20:23], v[164:167], v[152:155], v[20:23]
	v_mfma_f32_16x16x32_bf16 v[16:19], v[164:167], v[156:159], v[16:19]
	s_waitcnt lgkmcnt(0)
	v_mfma_f32_16x16x32_bf16 v[8:11], v[140:143], v[144:147], v[8:11]
	v_mfma_f32_16x16x32_bf16 v[4:7], v[140:143], v[148:151], v[4:7]
	v_mfma_f32_16x16x32_bf16 v[0:3], v[140:143], v[152:155], v[0:3]
	v_mfma_f32_16x16x32_bf16 v[12:15], v[140:143], v[156:159], v[12:15]
	ds_read_b128 v[140:143], v139
	v_add_u32_e32 v156, v168, v132
	ds_read_b128 v[144:147], v156 offset:16384
	ds_read_b128 v[148:151], v156 offset:18432
	ds_read_b128 v[152:155], v156 offset:20480
	ds_read_b128 v[156:159], v156 offset:22528
	ds_read_b128 v[160:163], v139 offset:2048
	ds_read_b128 v[164:167], v139 offset:4096
	s_waitcnt lgkmcnt(5)
	v_mfma_f32_16x16x32_bf16 v[60:63], v[140:143], v[144:147], v[60:63]
	s_waitcnt lgkmcnt(4)
	v_mfma_f32_16x16x32_bf16 v[56:59], v[140:143], v[148:151], v[56:59]
	s_waitcnt lgkmcnt(3)
	v_mfma_f32_16x16x32_bf16 v[52:55], v[140:143], v[152:155], v[52:55]
	s_waitcnt lgkmcnt(2)
	v_mfma_f32_16x16x32_bf16 v[48:51], v[140:143], v[156:159], v[48:51]
	ds_read_b128 v[140:143], v139 offset:6144
	s_waitcnt lgkmcnt(2)
	v_mfma_f32_16x16x32_bf16 v[44:47], v[160:163], v[144:147], v[44:47]
	v_mfma_f32_16x16x32_bf16 v[40:43], v[160:163], v[148:151], v[40:43]
	v_mfma_f32_16x16x32_bf16 v[36:39], v[160:163], v[152:155], v[36:39]
	v_mfma_f32_16x16x32_bf16 v[32:35], v[160:163], v[156:159], v[32:35]
	s_waitcnt lgkmcnt(1)
	v_mfma_f32_16x16x32_bf16 v[28:31], v[164:167], v[144:147], v[28:31]
	v_mfma_f32_16x16x32_bf16 v[24:27], v[164:167], v[148:151], v[24:27]
	v_mfma_f32_16x16x32_bf16 v[20:23], v[164:167], v[152:155], v[20:23]
	v_mfma_f32_16x16x32_bf16 v[16:19], v[164:167], v[156:159], v[16:19]
	s_waitcnt lgkmcnt(0)
	v_mfma_f32_16x16x32_bf16 v[8:11], v[140:143], v[144:147], v[8:11]
	v_mfma_f32_16x16x32_bf16 v[4:7], v[140:143], v[148:151], v[4:7]
	v_mfma_f32_16x16x32_bf16 v[0:3], v[140:143], v[152:155], v[0:3]
	v_mfma_f32_16x16x32_bf16 v[12:15], v[140:143], v[156:159], v[12:15]
	s_setprio 0
	s_cmpk_gt_u32 s9, 0x3bf
	s_cselect_b64 s[2:3], -1, 0
	s_and_b64 vcc, exec, s[2:3]
	s_cbranch_vccnz .LBB0_1809
	s_lshl_b32 s11, s10, 14
	s_xor_b32 s11, s11, 0x4000
	s_lshl_b32 s11, s11, 1
	v_add_u32_e32 v139, s11, v128
	s_waitcnt vmcnt(7)
	ds_write_b128 v139, v[64:67]
	s_waitcnt vmcnt(6)
	ds_write_b128 v139, v[68:71] offset:4096
	s_waitcnt vmcnt(5)
	ds_write_b128 v139, v[72:75] offset:8192
	s_waitcnt vmcnt(4)
	ds_write_b128 v139, v[76:79] offset:12288
	v_add3_u32 v139, s11, v133, v134
	s_waitcnt vmcnt(3)
	ds_write_b128 v139, v[232:235] offset:16384
	s_waitcnt vmcnt(2)
	ds_write_b128 v139, v[236:239] offset:16512
	v_add3_u32 v139, s11, v135, v136
	s_waitcnt vmcnt(1)
	ds_write_b128 v139, v[240:243] offset:16384
	v_add3_u32 v139, s11, v137, v138
	s_waitcnt vmcnt(0)
	ds_write_b128 v139, v[244:247] offset:16384
.LBB0_1809:
	s_cmpk_gt_u32 s9, 0x37f
	s_cbranch_scc1 .LBB0_1806
	v_lshl_add_u64 v[64:65], v[114:115], 0, v[112:113]
	v_lshl_add_u64 v[68:69], v[116:117], 0, v[112:113]
	v_lshl_add_u64 v[72:73], v[118:119], 0, v[112:113]
	v_lshl_add_u64 v[76:77], v[120:121], 0, v[112:113]
	global_load_dwordx4 v[64:67], v[64:65], off
	global_load_dwordx4 v[68:71], v[68:69], off
	global_load_dwordx4 v[72:75], v[72:73], off
	global_load_dwordx4 v[76:79], v[76:77], off
	global_load_dwordx4 v[232:235], v248, s[98:99]
	global_load_dwordx4 v[236:239], v248, s[98:99] offset:1024
	global_load_dwordx4 v[240:243], v248, s[98:99] offset:2048
	global_load_dwordx4 v[244:247], v248, s[98:99] offset:3072
	s_add_u32 s98, s98, 0x4000
	s_addc_u32 s99, s99, 0
	s_branch .LBB0_1806

	.amdhsa_kernel _Z11mega_kernelILb1EEv6Paramsii
		.amdhsa_group_segment_fixed_size 65552
		.amdhsa_private_segment_fixed_size 0
		.amdhsa_kernarg_size 808
		.amdhsa_user_sgpr_count 2
		.amdhsa_user_sgpr_dispatch_ptr 0
		.amdhsa_user_sgpr_queue_ptr 0
		.amdhsa_user_sgpr_kernarg_segment_ptr 1
		.amdhsa_user_sgpr_dispatch_id 0
		.amdhsa_user_sgpr_kernarg_preload_length 0
		.amdhsa_user_sgpr_kernarg_preload_offset 0
		.amdhsa_user_sgpr_private_segment_size 0
		.amdhsa_uses_dynamic_stack 0
		.amdhsa_enable_private_segment 0
		.amdhsa_system_sgpr_workgroup_id_x 1
		.amdhsa_system_sgpr_workgroup_id_y 0
		.amdhsa_system_sgpr_workgroup_id_z 0
		.amdhsa_system_sgpr_workgroup_info 0
		.amdhsa_system_vgpr_workitem_id 2
		.amdhsa_next_free_vgpr 256
		.amdhsa_next_free_sgpr 102
		.amdhsa_accum_offset 256
		.amdhsa_reserve_vcc 1
		.amdhsa_float_round_mode_32 0
		.amdhsa_float_round_mode_16_64 0
		.amdhsa_float_denorm_mode_32 3
		.amdhsa_float_denorm_mode_16_64 3
		.amdhsa_dx10_clamp 1
		.amdhsa_ieee_mode 1
		.amdhsa_fp16_overflow 0
		.amdhsa_tg_split 0
		.amdhsa_exception_fp_ieee_invalid_op 0
		.amdhsa_exception_fp_denorm_src 0
		.amdhsa_exception_fp_ieee_div_zero 0
		.amdhsa_exception_fp_ieee_overflow 0
		.amdhsa_exception_fp_ieee_underflow 0
		.amdhsa_exception_fp_ieee_inexact 0
		.amdhsa_exception_int_div_zero 0
	.end_amdhsa_kernel

amdhsa.kernels:
  - .agpr_count:     0
    .args:
      - .offset:         0
        .size:           544
        .value_kind:     by_value
      - .offset:         544
        .size:           4
        .value_kind:     by_value
      - .offset:         548
        .size:           4
        .value_kind:     by_value
      - .offset:         552
        .size:           4
        .value_kind:     hidden_block_count_x
      - .offset:         556
        .size:           4
        .value_kind:     hidden_block_count_y
      - .offset:         560
        .size:           4
        .value_kind:     hidden_block_count_z
      - .offset:         564
        .size:           2
        .value_kind:     hidden_group_size_x
      - .offset:         566
        .size:           2
        .value_kind:     hidden_group_size_y
      - .offset:         568
        .size:           2
        .value_kind:     hidden_group_size_z
      - .offset:         570
        .size:           2
        .value_kind:     hidden_remainder_x
      - .offset:         572
        .size:           2
        .value_kind:     hidden_remainder_y
      - .offset:         574
        .size:           2
        .value_kind:     hidden_remainder_z
      - .offset:         592
        .size:           8
        .value_kind:     hidden_global_offset_x
      - .offset:         600
        .size:           8
        .value_kind:     hidden_global_offset_y
      - .offset:         608
        .size:           8
        .value_kind:     hidden_global_offset_z
      - .offset:         616
        .size:           2
        .value_kind:     hidden_grid_dims
      - .offset:         640
        .size:           8
        .value_kind:     hidden_multigrid_sync_arg
    .group_segment_fixed_size: 65552
    .kernarg_segment_align: 8
    .kernarg_segment_size: 808
    .language:       OpenCL C
    .language_version:
      - 2
      - 0
    .max_flat_workgroup_size: 256
    .name:           _Z11mega_kernelILb1EEv6Paramsii
    .private_segment_fixed_size: 0
    .sgpr_count:     108
    .sgpr_spill_count: 140
    .symbol:         _Z11mega_kernelILb1EEv6Paramsii.kd
    .uniform_work_group_size: 1
    .uses_dynamic_stack: false
    .vgpr_count:     256
    .vgpr_spill_count: 0
    .wavefront_size: 64
